# prologue: non-temporal (nt) hint on the read-once f32 weight / x loads
# speedup vs baseline: 1.0238x; 1.0208x over previous
; #define LAS __attribute__((address_space(3)))
; #define LDS_WAIT() asm volatile("s_waitcnt lgkmcnt(0)" ::: "memory")
; __device__ __forceinline__ unsigned pk2(float lo, float hi) { return pg8::cvt_pk_bf16(lo, hi); }
; __device__ __forceinline__ void transpose_item(const float* W, int K, int N, bf16_t* WT, int mode, const float* kscale, LAS float* scr, int item, int lane) {
;     const int nblk = N / 32, kb = item / nblk, nb = item % nblk, k0 = 64 * kb, n0 = 32 * nb;
;     const int drow = (mode == 0 || mode == 3) ? n0 : ((n0 >> 7) * 256 + (n0 & 127) + (mode == 2 ? 128 : 0));
;     f32x4 t[8];
; #pragma unroll
;     for (int i = 0; i < 8; ++i) t[i] = *(const f32x4*)(W + (size_t)(k0 + 8 * i + (lane >> 3)) * N + n0 + 4 * (lane & 7));
; #pragma unroll
;     for (int i = 0; i < 8; ++i) { const int kk = 8 * i + (lane >> 3); const float sc = kscale ? kscale[k0 + kk] : 1.f; LAS float* d = scr + kk * 33 + 4 * (lane & 7);
;         d[0] = t[i][0] * sc; d[1] = t[i][1] * sc; d[2] = t[i][2] * sc; d[3] = t[i][3] * sc; }
;     LDS_WAIT(); asm volatile("" ::: "memory");
;     const int c = lane & 7;
; #pragma unroll
;     for (int j = 0; j < 4; ++j) { const int n = (lane >> 3) + 8 * j; const LAS float* s = scr + (8 * c) * 33 + n;
;         int dn = n;
;         if (mode == 3 && n0 >= 2048 && n0 < 6144) { const int d = (n0 & 127) + n; dn = ((d >> 4) & 3) * 32 + ((d >> 2) & 3) * 8 + (d >> 6) * 4 + (d & 3) - (n0 & 127); }
;         u32x4 o; o.x = pk2(s[0 * 33], s[1 * 33]); o.y = pk2(s[2 * 33], s[3 * 33]); o.z = pk2(s[4 * 33], s[5 * 33]); o.w = pk2(s[6 * 33], s[7 * 33]);
;         *(u32x4*)(WT + (size_t)(drow + dn) * K + k0 + 8 * c) = o; }
;     LDS_WAIT(); asm volatile("" ::: "memory");
; }
.LBB0_521:
	s_mul_hi_i32 s6, s27, 0xa0a0a0a1
	s_add_i32 s6, s6, s27
	s_lshr_b32 s7, s6, 31
	s_ashr_i32 s6, s6, 14
	s_add_i32 s18, s6, s7
	s_mul_i32 s6, s18, 0xffff9a00
	s_add_i32 s22, s27, s6
	s_ashr_i32 s19, s18, 31
	s_mul_i32 s7, s18, 0x6600000
	s_mul_hi_i32 s6, s18, 0x6600000
	s_add_u32 s29, s15, s7
	s_addc_u32 s28, s24, s6
	s_cmpk_gt_i32 s22, 0x1bff
	s_mov_b64 s[6:7], -1
	s_cbranch_scc0 .LBB0_551
	s_cmpk_gt_u32 s22, 0x23ff
	s_cbranch_scc0 .LBB0_548
	s_cmpk_gt_u32 s22, 0x39ff
	s_mul_hi_i32 s20, s18, 0x2c00000
	s_mul_i32 s21, s18, 0x2c00000
	s_cbranch_scc0 .LBB0_537
	s_cmpk_gt_u32 s22, 0x4fff
	s_cbranch_scc0 .LBB0_526
	s_load_dwordx2 s[6:7], s[16:17], 0x78
	v_lshlrev_b32_e32 v196, 2, v36
	v_mov_b32_e32 v31, v197
	v_add_u32_e32 v40, v39, v41
	v_add_u32_e32 v42, 0x420, v40
	s_waitcnt lgkmcnt(0)
	s_add_u32 s8, s6, s21
	s_addc_u32 s7, s7, s20
	s_and_b32 s9, s22, 0x7fffffc0
	s_and_b32 s6, s25, 0x7e0
	s_add_i32 s86, s9, 0xffffb000
	s_lshl_b32 s9, s6, 2
	s_add_u32 s8, s8, s9
	v_or_b32_e32 v30, s86, v34
	s_addc_u32 s9, s7, 0
	v_lshl_add_u64 v[32:33], s[8:9], 0, v[196:197]
	v_or_b32_e32 v196, 8, v30
	v_lshlrev_b64 v[4:5], 13, v[196:197]
	v_or_b32_e32 v196, 16, v30
	v_lshlrev_b64 v[10:11], 13, v[196:197]
	v_or_b32_e32 v196, 24, v30
	v_lshlrev_b64 v[12:13], 13, v[196:197]
	v_or_b32_e32 v196, 32, v30
	v_lshlrev_b64 v[18:19], 13, v[196:197]
	v_or_b32_e32 v196, 40, v30
	v_lshlrev_b64 v[2:3], 13, v[30:31]
	v_lshlrev_b64 v[20:21], 13, v[196:197]
	v_lshl_add_u64 v[2:3], v[32:33], 0, v[2:3]
	v_lshl_add_u64 v[6:7], v[32:33], 0, v[4:5]
	v_lshl_add_u64 v[10:11], v[32:33], 0, v[10:11]
	v_lshl_add_u64 v[14:15], v[32:33], 0, v[12:13]
	v_lshl_add_u64 v[18:19], v[32:33], 0, v[18:19]
	v_lshl_add_u64 v[22:23], v[32:33], 0, v[20:21]
	global_load_dwordx4 v[2:5], v[2:3], off nt
	s_nop 0
	global_load_dwordx4 v[6:9], v[6:7], off nt
	s_nop 0
	global_load_dwordx4 v[10:13], v[10:11], off nt
	s_nop 0
	global_load_dwordx4 v[14:17], v[14:15], off nt
	s_nop 0
	global_load_dwordx4 v[18:21], v[18:19], off nt
	s_nop 0
	global_load_dwordx4 v[22:25], v[22:23], off nt
	v_or_b32_e32 v196, 48, v30
	v_lshlrev_b64 v[26:27], 13, v[196:197]
	v_lshl_add_u64 v[26:27], v[32:33], 0, v[26:27]
	v_or_b32_e32 v196, 56, v30
	global_load_dwordx4 v[26:29], v[26:27], off nt
	v_lshlrev_b64 v[30:31], 13, v[196:197]
	v_lshl_add_u64 v[30:31], v[32:33], 0, v[30:31]
	global_load_dwordx4 v[30:33], v[30:31], off nt
	v_add_u32_e32 v43, 0x428, v40
	v_add_u32_e32 v44, 0x840, v40
	v_add_u32_e32 v54, 0x848, v40
	v_add_u32_e32 v55, 0xc60, v40
	v_add_u32_e32 v56, 0xc68, v40
	v_add_u32_e32 v57, 0x1080, v40
	v_add_u32_e32 v58, 0x1088, v40
	v_add_u32_e32 v59, 0x14a0, v40
	v_add_u32_e32 v60, 0x14a8, v40
	v_add_u32_e32 v61, 0x18c0, v40
	v_add_u32_e32 v62, 0x18c8, v40
	v_add_u32_e32 v63, 0x1ce0, v40
	v_add_u32_e32 v64, 0x1ce8, v40
	s_lshl_b64 s[8:9], s[86:87], 1
	s_add_u32 s8, s29, s8
	s_addc_u32 s9, s28, s9
	v_lshlrev_b32_e32 v196, 1, v38
	s_mov_b32 s86, 0x80000
	s_waitcnt vmcnt(0)
	ds_write2_b32 v40, v2, v3 offset1:1
	ds_write2_b32 v40, v4, v5 offset0:2 offset1:3
	ds_write2_b32 v42, v6, v7 offset1:1
	ds_write2_b32 v43, v8, v9 offset1:1
	ds_write2_b32 v44, v10, v11 offset1:1
	ds_write2_b32 v54, v12, v13 offset1:1
	ds_write2_b32 v55, v14, v15 offset1:1
	ds_write2_b32 v56, v16, v17 offset1:1
	ds_write2_b32 v57, v18, v19 offset1:1
	ds_write2_b32 v58, v20, v21 offset1:1
	ds_write2_b32 v59, v22, v23 offset1:1
	ds_write2_b32 v60, v24, v25 offset1:1
	ds_write2_b32 v61, v26, v27 offset1:1
	ds_write2_b32 v62, v28, v29 offset1:1
	ds_write2_b32 v63, v30, v31 offset1:1
	ds_write2_b32 v64, v32, v33 offset1:1
	s_waitcnt lgkmcnt(0)
	v_or_b32_e32 v6, s6, v34
	ds_read2_b32 v[2:3], v48 offset1:33
	v_mul_u32_u24_e32 v10, 0x1600, v6
	v_lshl_add_u64 v[8:9], s[8:9], 0, v[196:197]
	s_mov_b64 s[8:9], 0x5000000
	s_waitcnt lgkmcnt(0)
	v_cvt_pk_bf16_f32 v2, v2, v3
	ds_read2_b32 v[4:5], v48 offset0:66 offset1:99
	v_lshlrev_b32_e32 v196, 1, v10
	v_lshl_add_u64 v[8:9], v[8:9], 0, s[8:9]
	s_waitcnt lgkmcnt(0)
	v_cvt_pk_bf16_f32 v3, v4, v5
	ds_read2_b32 v[4:5], v48 offset0:132 offset1:165
	v_lshl_add_u64 v[10:11], v[8:9], 0, v[196:197]
	s_waitcnt lgkmcnt(0)
	v_cvt_pk_bf16_f32 v4, v4, v5
	ds_read2_b32 v[6:7], v48 offset0:198 offset1:231
	s_waitcnt lgkmcnt(0)
	v_cvt_pk_bf16_f32 v5, v6, v7
	global_store_dwordx4 v[10:11], v[2:5], off
	v_or_b32_e32 v10, s6, v45
	v_mul_u32_u24_e32 v10, 0x1600, v10
	ds_read2_b32 v[6:7], v48 offset0:8 offset1:41
	s_waitcnt lgkmcnt(0)
	v_cvt_pk_bf16_f32 v2, v6, v7
	ds_read2_b32 v[4:5], v48 offset0:74 offset1:107
	v_lshlrev_b32_e32 v196, 1, v10
	s_waitcnt lgkmcnt(0)
	v_cvt_pk_bf16_f32 v3, v4, v5
	ds_read2_b32 v[4:5], v48 offset0:140 offset1:173
	v_lshl_add_u64 v[10:11], v[8:9], 0, v[196:197]
	s_waitcnt lgkmcnt(0)
	v_cvt_pk_bf16_f32 v4, v4, v5
	ds_read2_b32 v[6:7], v48 offset0:206 offset1:239
	s_waitcnt lgkmcnt(0)
	v_cvt_pk_bf16_f32 v5, v6, v7
	global_store_dwordx4 v[10:11], v[2:5], off
	v_or_b32_e32 v10, s6, v46
	ds_read2_b32 v[6:7], v48 offset0:16 offset1:49
	s_waitcnt lgkmcnt(0)
	v_cvt_pk_bf16_f32 v2, v6, v7
	ds_read2_b32 v[4:5], v48 offset0:82 offset1:115
	v_mul_u32_u24_e32 v10, 0x1600, v10
	s_waitcnt lgkmcnt(0)
	v_cvt_pk_bf16_f32 v3, v4, v5
	ds_read2_b32 v[4:5], v48 offset0:148 offset1:181
	v_lshlrev_b32_e32 v196, 1, v10
	s_waitcnt lgkmcnt(0)
	v_cvt_pk_bf16_f32 v4, v4, v5
	ds_read2_b32 v[6:7], v48 offset0:214 offset1:247
	s_waitcnt lgkmcnt(0)
	v_cvt_pk_bf16_f32 v5, v6, v7
	v_lshl_add_u64 v[10:11], v[8:9], 0, v[196:197]
	ds_read2_b32 v[6:7], v48 offset0:24 offset1:57
	global_store_dwordx4 v[10:11], v[2:5], off
	s_waitcnt lgkmcnt(0)
	s_nop 0
	v_cvt_pk_bf16_f32 v2, v6, v7
	ds_read2_b32 v[4:5], v48 offset0:90 offset1:123
	s_waitcnt lgkmcnt(0)
	v_cvt_pk_bf16_f32 v3, v4, v5
	ds_read2_b32 v[4:5], v48 offset0:156 offset1:189
	s_waitcnt lgkmcnt(0)
	v_cvt_pk_bf16_f32 v4, v4, v5
	v_or_b32_e32 v5, s6, v47
	v_mul_u32_u24_e32 v5, 0x1600, v5
	ds_read2_b32 v[6:7], v48 offset0:222 offset1:255
	v_lshlrev_b32_e32 v196, 1, v5
	s_waitcnt lgkmcnt(0)
	v_cvt_pk_bf16_f32 v5, v6, v7
	v_lshl_add_u64 v[6:7], v[8:9], 0, v[196:197]
	global_store_dwordx4 v[6:7], v[2:5], off
	s_waitcnt lgkmcnt(0)
	s_mov_b64 s[6:7], 0
; #define LAS __attribute__((address_space(3)))
; #define LDS_WAIT() asm volatile("s_waitcnt lgkmcnt(0)" ::: "memory")
; __device__ __forceinline__ void transpose_item(const float* W, int K, int N, bf16_t* WT, int mode, const float* kscale, LAS float* scr, int item, int lane) {
;     const int nblk = N / 32, kb = item / nblk, nb = item % nblk, k0 = 64 * kb, n0 = 32 * nb;
;     const int drow = (mode == 0 || mode == 3) ? n0 : ((n0 >> 7) * 256 + (n0 & 127) + (mode == 2 ? 128 : 0));
;     f32x4 t[8];
; #pragma unroll
;     for (int i = 0; i < 8; ++i) t[i] = *(const f32x4*)(W + (size_t)(k0 + 8 * i + (lane >> 3)) * N + n0 + 4 * (lane & 7));
; #pragma unroll
;     for (int i = 0; i < 8; ++i) { const int kk = 8 * i + (lane >> 3); const float sc = kscale ? kscale[k0 + kk] : 1.f; LAS float* d = scr + kk * 33 + 4 * (lane & 7);
;         d[0] = t[i][0] * sc; d[1] = t[i][1] * sc; d[2] = t[i][2] * sc; d[3] = t[i][3] * sc; }
;     LDS_WAIT(); asm volatile("" ::: "memory");
.LBB0_526:
	s_andn2_b64 vcc, exec, s[6:7]
	s_cbranch_vccnz .LBB0_536
	s_load_dwordx2 s[6:7], s[16:17], 0x70
	s_load_dwordx2 s[34:35], s[16:17], 0x60
	v_lshlrev_b32_e32 v196, 2, v36
	v_mov_b32_e32 v40, 1.0
	v_mov_b32_e32 v42, 1.0
	s_waitcnt lgkmcnt(0)
	s_add_u32 s10, s6, s21
	s_addc_u32 s11, s7, s20
	s_lshl_b64 s[6:7], s[18:19], 13
	s_add_u32 s8, s34, s6
	s_addc_u32 s9, s35, s7
	s_add_i32 s6, s22, 0xc600
	s_and_b32 s7, s6, 0xffff
	s_mul_i32 s7, s7, 0xba2f
	s_lshr_b32 s7, s7, 23
	s_mul_i32 s30, s7, 0xb0
	s_sub_i32 s6, s6, s30
	s_and_b32 s30, s6, 0xffff
	s_lshl_b32 s23, s7, 6
	s_lshl_b32 s6, s30, 7
	s_add_u32 s6, s10, s6
	v_or_b32_e32 v44, s23, v34
	s_addc_u32 s7, s11, 0
	v_lshl_add_u64 v[2:3], s[6:7], 0, v[196:197]
	s_movk_i32 s6, 0x5800
	v_mul_u32_u24_e32 v6, 0x1600, v44
	v_mad_u64_u32 v[4:5], s[6:7], v44, s6, v[2:3]
	v_lshlrev_b32_e32 v196, 2, v6
	v_lshl_add_u64 v[2:3], v[2:3], 0, v[196:197]
	s_mov_b32 s6, 0x2c000
	v_add_co_u32_e32 v6, vcc, s6, v2
	s_mov_b32 s6, 0x58000
	s_nop 0
	v_addc_co_u32_e32 v7, vcc, 0, v3, vcc
	global_load_dwordx4 v[30:33], v[4:5], off nt
	global_load_dwordx4 v[26:29], v[6:7], off nt
	v_add_co_u32_e32 v4, vcc, s6, v2
	s_mov_b32 s6, 0x84000
	s_nop 0
	v_addc_co_u32_e32 v5, vcc, 0, v3, vcc
	v_add_co_u32_e32 v6, vcc, s6, v2
	s_mov_b32 s6, 0xb0000
	s_nop 0
	v_addc_co_u32_e32 v7, vcc, 0, v3, vcc
	global_load_dwordx4 v[22:25], v[4:5], off nt
	global_load_dwordx4 v[18:21], v[6:7], off nt
	v_add_co_u32_e32 v4, vcc, s6, v2
	s_mov_b32 s6, 0xdc000
	s_nop 0
	v_addc_co_u32_e32 v5, vcc, 0, v3, vcc
	v_add_co_u32_e32 v6, vcc, s6, v2
	s_cmp_lg_u64 s[34:35], 0
	s_nop 0
	v_addc_co_u32_e32 v7, vcc, 0, v3, vcc
	global_load_dwordx4 v[14:17], v[4:5], off nt
	global_load_dwordx4 v[10:13], v[6:7], off nt
	v_add_co_u32_e32 v4, vcc, 0x108000, v2
	s_cselect_b64 s[10:11], -1, 0
	s_nop 0
	v_addc_co_u32_e32 v5, vcc, 0, v3, vcc
	v_add_co_u32_e32 v2, vcc, 0x134000, v2
	s_cmp_eq_u64 s[34:35], 0
	s_nop 0
	v_addc_co_u32_e32 v3, vcc, 0, v3, vcc
	global_load_dwordx4 v[6:9], v[4:5], off nt
	s_nop 0
	global_load_dwordx4 v[2:5], v[2:3], off nt
	v_add_lshl_u32 v43, v34, s23, 2
	s_cbranch_scc1 .LBB0_529
	v_lshlrev_b32_e32 v42, 2, v44
	global_load_dword v44, v42, s[8:9]
	s_nop 0
	global_load_dword v42, v43, s[8:9] offset:32
	global_load_dword v100, v43, s[8:9] offset:64
	global_load_dword v101, v43, s[8:9] offset:96
	global_load_dword v102, v43, s[8:9] offset:128
	global_load_dword v103, v43, s[8:9] offset:160
	global_load_dword v104, v43, s[8:9] offset:192
	global_load_dword v105, v43, s[8:9] offset:224
	s_waitcnt vmcnt(0)
	v_pk_mul_f32 v[30:31], v[30:31], v[44:45] op_sel_hi:[1,0]
	v_pk_mul_f32 v[32:33], v[32:33], v[44:45] op_sel_hi:[1,0]

; #define LAS __attribute__((address_space(3)))
; #define LDS_WAIT() asm volatile("s_waitcnt lgkmcnt(0)" ::: "memory")
; __device__ __forceinline__ void transpose_item(const float* W, int K, int N, bf16_t* WT, int mode, const float* kscale, LAS float* scr, int item, int lane) {
;     const int nblk = N / 32, kb = item / nblk, nb = item % nblk, k0 = 64 * kb, n0 = 32 * nb;
;     const int drow = (mode == 0 || mode == 3) ? n0 : ((n0 >> 7) * 256 + (n0 & 127) + (mode == 2 ? 128 : 0));
;     f32x4 t[8];
; #pragma unroll
;     for (int i = 0; i < 8; ++i) t[i] = *(const f32x4*)(W + (size_t)(k0 + 8 * i + (lane >> 3)) * N + n0 + 4 * (lane & 7));
; #pragma unroll
;     for (int i = 0; i < 8; ++i) { const int kk = 8 * i + (lane >> 3); const float sc = kscale ? kscale[k0 + kk] : 1.f; LAS float* d = scr + kk * 33 + 4 * (lane & 7);
;         d[0] = t[i][0] * sc; d[1] = t[i][1] * sc; d[2] = t[i][2] * sc; d[3] = t[i][3] * sc; }
;     LDS_WAIT(); asm volatile("" ::: "memory");
.LBB0_537:
	s_andn2_b64 vcc, exec, s[6:7]
	s_cbranch_vccnz .LBB0_547
	s_load_dwordx4 s[8:11], s[16:17], 0x60
	v_lshlrev_b32_e32 v196, 2, v36
	v_mov_b32_e32 v40, 1.0
	v_mov_b32_e32 v42, 1.0
	s_waitcnt lgkmcnt(0)
	s_add_u32 s21, s10, s21
	s_addc_u32 s20, s11, s20
	s_lshl_b64 s[6:7], s[18:19], 13
	s_add_u32 s10, s8, s6
	s_addc_u32 s11, s9, s7
	s_add_i32 s6, s22, 0xdc00
	s_and_b32 s7, s6, 0xffff
	s_mul_i32 s7, s7, 0xba2f
	s_lshr_b32 s7, s7, 23
	s_mul_i32 s30, s7, 0xb0
	s_sub_i32 s6, s6, s30
	s_and_b32 s30, s6, 0xffff
	s_lshl_b32 s23, s7, 6
	s_lshl_b32 s6, s30, 7
	s_add_u32 s6, s21, s6
	v_or_b32_e32 v44, s23, v34
	s_addc_u32 s7, s20, 0
	v_lshl_add_u64 v[2:3], s[6:7], 0, v[196:197]
	s_movk_i32 s6, 0x5800
	v_mul_u32_u24_e32 v6, 0x1600, v44
	v_mad_u64_u32 v[4:5], s[6:7], v44, s6, v[2:3]
	v_lshlrev_b32_e32 v196, 2, v6
	v_lshl_add_u64 v[2:3], v[2:3], 0, v[196:197]
	s_mov_b32 s6, 0x2c000
	v_add_co_u32_e32 v6, vcc, s6, v2
	s_mov_b32 s6, 0x58000
	s_nop 0
	v_addc_co_u32_e32 v7, vcc, 0, v3, vcc
	global_load_dwordx4 v[30:33], v[4:5], off nt
	global_load_dwordx4 v[26:29], v[6:7], off nt
	v_add_co_u32_e32 v4, vcc, s6, v2
	s_mov_b32 s6, 0x84000
	s_nop 0
	v_addc_co_u32_e32 v5, vcc, 0, v3, vcc
	v_add_co_u32_e32 v6, vcc, s6, v2
	s_mov_b32 s6, 0xb0000
	s_nop 0
	v_addc_co_u32_e32 v7, vcc, 0, v3, vcc
	global_load_dwordx4 v[22:25], v[4:5], off nt
	global_load_dwordx4 v[18:21], v[6:7], off nt
	v_add_co_u32_e32 v4, vcc, s6, v2
	s_mov_b32 s6, 0xdc000
	s_nop 0
	v_addc_co_u32_e32 v5, vcc, 0, v3, vcc
	v_add_co_u32_e32 v6, vcc, s6, v2
	s_cmp_lg_u64 s[8:9], 0
	s_nop 0
	v_addc_co_u32_e32 v7, vcc, 0, v3, vcc
	global_load_dwordx4 v[14:17], v[4:5], off nt
	global_load_dwordx4 v[10:13], v[6:7], off nt
	v_add_co_u32_e32 v4, vcc, 0x108000, v2
	s_cselect_b64 s[20:21], -1, 0
	s_nop 0
	v_addc_co_u32_e32 v5, vcc, 0, v3, vcc
	v_add_co_u32_e32 v2, vcc, 0x134000, v2
	s_cmp_eq_u64 s[8:9], 0
	s_nop 0
	v_addc_co_u32_e32 v3, vcc, 0, v3, vcc
	global_load_dwordx4 v[6:9], v[4:5], off nt
	s_nop 0
	global_load_dwordx4 v[2:5], v[2:3], off nt
	v_add_lshl_u32 v43, v34, s23, 2
	s_cbranch_scc1 .LBB0_540
	v_lshlrev_b32_e32 v42, 2, v44
	global_load_dword v44, v42, s[10:11]
	s_nop 0
	global_load_dword v42, v43, s[10:11] offset:32
	global_load_dword v100, v43, s[10:11] offset:64
	global_load_dword v101, v43, s[10:11] offset:96
	global_load_dword v102, v43, s[10:11] offset:128
	global_load_dword v103, v43, s[10:11] offset:160
	global_load_dword v104, v43, s[10:11] offset:192
	global_load_dword v105, v43, s[10:11] offset:224
	s_waitcnt vmcnt(0)
	v_pk_mul_f32 v[30:31], v[30:31], v[44:45] op_sel_hi:[1,0]
	v_pk_mul_f32 v[32:33], v[32:33], v[44:45] op_sel_hi:[1,0]

; #define LAS __attribute__((address_space(3)))
; #define LDS_WAIT() asm volatile("s_waitcnt lgkmcnt(0)" ::: "memory")
; __device__ __forceinline__ unsigned pk2(float lo, float hi) { return pg8::cvt_pk_bf16(lo, hi); }
; __device__ __forceinline__ void transpose_item(const float* W, int K, int N, bf16_t* WT, int mode, const float* kscale, LAS float* scr, int item, int lane) {
;     const int nblk = N / 32, kb = item / nblk, nb = item % nblk, k0 = 64 * kb, n0 = 32 * nb;
;     const int drow = (mode == 0 || mode == 3) ? n0 : ((n0 >> 7) * 256 + (n0 & 127) + (mode == 2 ? 128 : 0));
;     f32x4 t[8];
; #pragma unroll
;     for (int i = 0; i < 8; ++i) t[i] = *(const f32x4*)(W + (size_t)(k0 + 8 * i + (lane >> 3)) * N + n0 + 4 * (lane & 7));
; #pragma unroll
;     for (int i = 0; i < 8; ++i) { const int kk = 8 * i + (lane >> 3); const float sc = kscale ? kscale[k0 + kk] : 1.f; LAS float* d = scr + kk * 33 + 4 * (lane & 7);
;         d[0] = t[i][0] * sc; d[1] = t[i][1] * sc; d[2] = t[i][2] * sc; d[3] = t[i][3] * sc; }
;     LDS_WAIT(); asm volatile("" ::: "memory");
;     const int c = lane & 7;
; #pragma unroll
;     for (int j = 0; j < 4; ++j) { const int n = (lane >> 3) + 8 * j; const LAS float* s = scr + (8 * c) * 33 + n;
;         int dn = n;
;         if (mode == 3 && n0 >= 2048 && n0 < 6144) { const int d = (n0 & 127) + n; dn = ((d >> 4) & 3) * 32 + ((d >> 2) & 3) * 8 + (d >> 6) * 4 + (d & 3) - (n0 & 127); }
;         u32x4 o; o.x = pk2(s[0 * 33], s[1 * 33]); o.y = pk2(s[2 * 33], s[3 * 33]); o.z = pk2(s[4 * 33], s[5 * 33]); o.w = pk2(s[6 * 33], s[7 * 33]);
;         *(u32x4*)(WT + (size_t)(drow + dn) * K + k0 + 8 * c) = o; }
;     LDS_WAIT(); asm volatile("" ::: "memory");
; }
.LBB0_548:
	s_andn2_b64 vcc, exec, s[6:7]
	s_cbranch_vccnz .LBB0_550
	s_load_dwordx2 s[6:7], s[16:17], 0x58
	s_add_i32 s10, s22, 0xe400
	s_lshl_b64 s[8:9], s[18:19], 24
	v_lshlrev_b32_e32 v196, 2, v36
	v_add_u32_e32 v40, v39, v41
	s_waitcnt lgkmcnt(0)
	s_add_u32 s8, s6, s8
	s_addc_u32 s7, s7, s9
	s_and_b32 s6, s25, 0x7e0
	s_and_b32 s10, s10, 0xffc0
	s_lshl_b32 s9, s6, 2
	s_add_u32 s8, s8, s9
	v_or_b32_e32 v4, s10, v34
	s_addc_u32 s9, s7, 0
	v_lshl_add_u64 v[2:3], s[8:9], 0, v[196:197]
	v_lshlrev_b32_e32 v196, 13, v4
	v_lshl_add_u64 v[30:31], v[2:3], 0, v[196:197]
	s_mov_b32 s7, 0x10000
	v_add_co_u32_e32 v6, vcc, s7, v30
	s_mov_b32 s7, 0x20000
	s_nop 0
	v_addc_co_u32_e32 v7, vcc, 0, v31, vcc
	v_add_co_u32_e32 v10, vcc, s7, v30
	s_mov_b32 s7, 0x30000
	s_nop 0
	v_addc_co_u32_e32 v11, vcc, 0, v31, vcc
	v_add_co_u32_e32 v14, vcc, s7, v30
	s_mov_b32 s7, 0x40000
	s_nop 0
	v_addc_co_u32_e32 v15, vcc, 0, v31, vcc
	v_add_co_u32_e32 v18, vcc, s7, v30
	s_mov_b32 s7, 0x50000
	s_nop 0
	v_addc_co_u32_e32 v19, vcc, 0, v31, vcc
	v_add_co_u32_e32 v22, vcc, s7, v30
	global_load_dwordx4 v[2:5], v[30:31], off nt
	s_nop 0
	global_load_dwordx4 v[6:9], v[6:7], off nt
	v_addc_co_u32_e32 v23, vcc, 0, v31, vcc
	global_load_dwordx4 v[10:13], v[10:11], off nt
	s_nop 0
	global_load_dwordx4 v[14:17], v[14:15], off nt
	s_nop 0
	global_load_dwordx4 v[18:21], v[18:19], off nt
	s_nop 0
	global_load_dwordx4 v[22:25], v[22:23], off nt
	s_mov_b32 s7, 0x60000
	v_add_co_u32_e32 v26, vcc, s7, v30
	s_mov_b32 s7, 0x70000
	s_nop 0
	v_addc_co_u32_e32 v27, vcc, 0, v31, vcc
	global_load_dwordx4 v[26:29], v[26:27], off nt
	v_add_co_u32_e32 v30, vcc, s7, v30
	v_add_u32_e32 v42, 0x420, v40
	s_nop 0
	v_addc_co_u32_e32 v31, vcc, 0, v31, vcc
	global_load_dwordx4 v[30:33], v[30:31], off nt
	v_add_u32_e32 v43, 0x428, v40
	v_add_u32_e32 v44, 0x840, v40
	v_add_u32_e32 v54, 0x848, v40
	v_add_u32_e32 v55, 0xc60, v40
	v_add_u32_e32 v56, 0xc68, v40
	v_add_u32_e32 v57, 0x1080, v40
	v_add_u32_e32 v58, 0x1088, v40
	v_add_u32_e32 v59, 0x14a0, v40
	v_add_u32_e32 v60, 0x14a8, v40
	v_add_u32_e32 v61, 0x18c0, v40
	v_add_u32_e32 v62, 0x18c8, v40
	v_add_u32_e32 v63, 0x1ce0, v40
	v_add_u32_e32 v64, 0x1ce8, v40
	s_lshl_b32 s7, s10, 1
	s_add_u32 s8, s29, s7
	s_addc_u32 s9, s28, 0
	v_lshlrev_b32_e32 v196, 1, v38
	s_waitcnt vmcnt(0)
	ds_write2_b32 v40, v2, v3 offset1:1
	ds_write2_b32 v40, v4, v5 offset0:2 offset1:3
	ds_write2_b32 v42, v6, v7 offset1:1
	ds_write2_b32 v43, v8, v9 offset1:1
	ds_write2_b32 v44, v10, v11 offset1:1
	ds_write2_b32 v54, v12, v13 offset1:1
	ds_write2_b32 v55, v14, v15 offset1:1
	ds_write2_b32 v56, v16, v17 offset1:1
	ds_write2_b32 v57, v18, v19 offset1:1
	ds_write2_b32 v58, v20, v21 offset1:1
	ds_write2_b32 v59, v22, v23 offset1:1
	ds_write2_b32 v60, v24, v25 offset1:1
	ds_write2_b32 v61, v26, v27 offset1:1
	ds_write2_b32 v62, v28, v29 offset1:1
	ds_write2_b32 v63, v30, v31 offset1:1
	ds_write2_b32 v64, v32, v33 offset1:1
	s_waitcnt lgkmcnt(0)
	ds_read2_b32 v[2:3], v48 offset1:33
	s_waitcnt lgkmcnt(0)
	v_cvt_pk_bf16_f32 v2, v2, v3
	ds_read2_b32 v[4:5], v48 offset0:66 offset1:99
	v_or_b32_e32 v10, s6, v34
	v_lshl_add_u64 v[8:9], s[8:9], 0, v[196:197]
	s_mov_b64 s[8:9], 0x1c00000
	s_waitcnt lgkmcnt(0)
	v_cvt_pk_bf16_f32 v3, v4, v5
	ds_read2_b32 v[4:5], v48 offset0:132 offset1:165
	v_lshlrev_b32_e32 v196, 12, v10
	v_lshl_add_u64 v[8:9], v[8:9], 0, s[8:9]
	s_waitcnt lgkmcnt(0)
	v_cvt_pk_bf16_f32 v4, v4, v5
	ds_read2_b32 v[6:7], v48 offset0:198 offset1:231
	s_waitcnt lgkmcnt(0)
	v_cvt_pk_bf16_f32 v5, v6, v7
	v_lshl_add_u64 v[10:11], v[8:9], 0, v[196:197]
	ds_read2_b32 v[6:7], v48 offset0:8 offset1:41
	global_store_dwordx4 v[10:11], v[2:5], off
	v_or_b32_e32 v10, s6, v45
	v_lshlrev_b32_e32 v196, 12, v10
	s_waitcnt lgkmcnt(0)
	v_cvt_pk_bf16_f32 v2, v6, v7
	ds_read2_b32 v[4:5], v48 offset0:74 offset1:107
	s_waitcnt lgkmcnt(0)
	v_cvt_pk_bf16_f32 v3, v4, v5
	ds_read2_b32 v[4:5], v48 offset0:140 offset1:173
	s_waitcnt lgkmcnt(0)
	v_cvt_pk_bf16_f32 v4, v4, v5
	ds_read2_b32 v[6:7], v48 offset0:206 offset1:239
	s_waitcnt lgkmcnt(0)
	v_cvt_pk_bf16_f32 v5, v6, v7
	v_lshl_add_u64 v[10:11], v[8:9], 0, v[196:197]
	ds_read2_b32 v[6:7], v48 offset0:16 offset1:49
	global_store_dwordx4 v[10:11], v[2:5], off
	v_or_b32_e32 v10, s6, v46
	v_lshlrev_b32_e32 v196, 12, v10
	s_waitcnt lgkmcnt(0)
	v_cvt_pk_bf16_f32 v2, v6, v7
	ds_read2_b32 v[4:5], v48 offset0:82 offset1:115
	s_waitcnt lgkmcnt(0)
	v_cvt_pk_bf16_f32 v3, v4, v5
	ds_read2_b32 v[4:5], v48 offset0:148 offset1:181
	s_waitcnt lgkmcnt(0)
	v_cvt_pk_bf16_f32 v4, v4, v5
	ds_read2_b32 v[6:7], v48 offset0:214 offset1:247
	s_waitcnt lgkmcnt(0)
	v_cvt_pk_bf16_f32 v5, v6, v7
	v_lshl_add_u64 v[10:11], v[8:9], 0, v[196:197]
	ds_read2_b32 v[6:7], v48 offset0:24 offset1:57
	global_store_dwordx4 v[10:11], v[2:5], off
	s_waitcnt lgkmcnt(0)
	s_nop 0
	v_cvt_pk_bf16_f32 v2, v6, v7
	ds_read2_b32 v[4:5], v48 offset0:90 offset1:123
	s_waitcnt lgkmcnt(0)
	v_cvt_pk_bf16_f32 v3, v4, v5
	ds_read2_b32 v[4:5], v48 offset0:156 offset1:189
	s_waitcnt lgkmcnt(0)
	v_cvt_pk_bf16_f32 v4, v4, v5
	v_or_b32_e32 v5, s6, v47
	ds_read2_b32 v[6:7], v48 offset0:222 offset1:255
	v_lshlrev_b32_e32 v196, 12, v5
	s_waitcnt lgkmcnt(0)
	v_cvt_pk_bf16_f32 v5, v6, v7
	v_lshl_add_u64 v[6:7], v[8:9], 0, v[196:197]
	global_store_dwordx4 v[6:7], v[2:5], off
	s_waitcnt lgkmcnt(0)

; #define LAS __attribute__((address_space(3)))
; #define LDS_WAIT() asm volatile("s_waitcnt lgkmcnt(0)" ::: "memory")
; __device__ __forceinline__ void transpose_item(const float* W, int K, int N, bf16_t* WT, int mode, const float* kscale, LAS float* scr, int item, int lane) {
;     const int nblk = N / 32, kb = item / nblk, nb = item % nblk, k0 = 64 * kb, n0 = 32 * nb;
;     const int drow = (mode == 0 || mode == 3) ? n0 : ((n0 >> 7) * 256 + (n0 & 127) + (mode == 2 ? 128 : 0));
;     f32x4 t[8];
; #pragma unroll
;     for (int i = 0; i < 8; ++i) t[i] = *(const f32x4*)(W + (size_t)(k0 + 8 * i + (lane >> 3)) * N + n0 + 4 * (lane & 7));
; #pragma unroll
;     for (int i = 0; i < 8; ++i) { const int kk = 8 * i + (lane >> 3); const float sc = kscale ? kscale[k0 + kk] : 1.f; LAS float* d = scr + kk * 33 + 4 * (lane & 7);
;         d[0] = t[i][0] * sc; d[1] = t[i][1] * sc; d[2] = t[i][2] * sc; d[3] = t[i][3] * sc; }
;     LDS_WAIT(); asm volatile("" ::: "memory");
.LBB0_551:
	s_andn2_b64 vcc, exec, s[6:7]
	s_cbranch_vccnz .LBB0_520
	s_load_dwordx4 s[8:11], s[16:17], 0x8
	s_mul_i32 s7, s18, 0x3800000
	s_mul_hi_i32 s6, s18, 0x3800000
	s_mul_hi_i32 s23, s22, 0x92492493
	v_lshlrev_b32_e32 v196, 2, v36
	s_waitcnt lgkmcnt(0)
	s_add_u32 s31, s10, s7
	s_addc_u32 s34, s11, s6
	s_lshl_b64 s[6:7], s[18:19], 13
	s_add_u32 s20, s8, s6
	s_addc_u32 s21, s9, s7
	s_add_i32 s23, s23, s22
	s_lshr_b32 s6, s23, 31
	s_ashr_i32 s7, s23, 7
	s_add_i32 s6, s7, s6
	s_mul_i32 s7, s6, 0xe0
	s_sub_i32 s30, s22, s7
	s_lshl_b32 s10, s30, 5
	s_ashr_i32 s11, s10, 31
	s_lshl_b32 s18, s6, 6
	s_lshl_b64 s[6:7], s[10:11], 2
	s_add_u32 s6, s31, s6
	v_or_b32_e32 v42, s18, v34
	s_addc_u32 s7, s34, s7
	v_lshl_add_u64 v[2:3], s[6:7], 0, v[196:197]
	s_movk_i32 s11, 0x7000
	v_or_b32_e32 v6, 8, v42
	v_mad_i64_i32 v[4:5], s[6:7], v42, s11, v[2:3]
	v_mad_i64_i32 v[6:7], s[6:7], v6, s11, v[2:3]
	global_load_dwordx4 v[30:33], v[4:5], off nt
	global_load_dwordx4 v[26:29], v[6:7], off nt
	v_or_b32_e32 v4, 16, v42
	v_or_b32_e32 v6, 24, v42
	v_mad_i64_i32 v[4:5], s[6:7], v4, s11, v[2:3]
	v_mad_i64_i32 v[6:7], s[6:7], v6, s11, v[2:3]
	global_load_dwordx4 v[22:25], v[4:5], off nt
	global_load_dwordx4 v[18:21], v[6:7], off nt
	v_or_b32_e32 v4, 32, v42
	v_or_b32_e32 v6, 40, v42
	v_mad_i64_i32 v[4:5], s[6:7], v4, s11, v[2:3]
	v_mad_i64_i32 v[6:7], s[6:7], v6, s11, v[2:3]
	global_load_dwordx4 v[14:17], v[4:5], off nt
	global_load_dwordx4 v[10:13], v[6:7], off nt
	v_or_b32_e32 v4, 48, v42
	v_or_b32_e32 v6, 56, v42
	v_mad_i64_i32 v[4:5], s[6:7], v4, s11, v[2:3]
	v_mad_i64_i32 v[2:3], s[6:7], v6, s11, v[2:3]
	global_load_dwordx4 v[6:9], v[4:5], off nt
	s_nop 0
	global_load_dwordx4 v[2:5], v[2:3], off nt
	s_cmp_lg_u64 s[8:9], 0
	s_cselect_b64 s[22:23], -1, 0
	s_cmp_eq_u64 s[8:9], 0
	v_mov_b32_e32 v40, 1.0
	v_mov_b32_e32 v44, 1.0
	s_cbranch_scc1 .LBB0_554
	v_ashrrev_i32_e32 v43, 31, v42
	s_ashr_i32 s19, s18, 31
	v_lshl_add_u64 v[42:43], v[42:43], 2, s[20:21]
	v_lshl_add_u64 v[54:55], s[18:19], 0, v[34:35]
	global_load_dword v42, v[42:43], off
	v_lshl_add_u64 v[54:55], v[54:55], 2, s[20:21]
	global_load_dword v44, v[54:55], off offset:32
	s_waitcnt vmcnt(0)
	v_pk_mul_f32 v[30:31], v[30:31], v[42:43] op_sel_hi:[1,0]
	v_pk_mul_f32 v[32:33], v[32:33], v[42:43] op_sel_hi:[1,0]

; __device__ __forceinline__ unsigned pk2(float lo, float hi) { return pg8::cvt_pk_bf16(lo, hi); }
; __device__ __forceinline__ void convert_rows(const float* X, bf16_t* out, float* rsq, int gw, int ngw, int lane) {
;     for (int m = gw; m < M; m += ngw) {
;         const f32x4* xr = (const f32x4*)(X + (size_t)m * DM) + lane;
;         f32x4 v[8]; float s = 0.f;
; #pragma unroll
;         for (int j = 0; j < 8; ++j) { v[j] = xr[64 * j]; s += (v[j].x * v[j].x + v[j].y * v[j].y) + (v[j].z * v[j].z + v[j].w * v[j].w); }
;         s = wave_sum(s); if (lane == 0) rsq[m] = s;
;         u32x2* o8 = (u32x2*)(out + (size_t)m * DM) + lane;
; #pragma unroll
;         for (int j = 0; j < 8; ++j) { u32x2 w; w.x = pk2(v[j].x, v[j].y); w.y = pk2(v[j].z, v[j].w); o8[64 * j] = w; }
;     }
; }
.LBB0_569:
	global_load_dwordx4 v[30:33], v[34:35], off offset:-4096 nt
	global_load_dwordx4 v[2:5], v[34:35], off offset:-3072 nt
	global_load_dwordx4 v[6:9], v[34:35], off offset:-2048 nt
	global_load_dwordx4 v[10:13], v[34:35], off offset:-1024 nt
	global_load_dwordx4 v[14:17], v[34:35], off nt
	global_load_dwordx4 v[18:21], v[34:35], off offset:1024 nt
	global_load_dwordx4 v[22:25], v[34:35], off offset:2048 nt
	global_load_dwordx4 v[26:29], v[34:35], off offset:3072 nt
	s_waitcnt vmcnt(0)
	v_mul_f32_e32 v1, v31, v31
	v_mul_f32_e32 v44, v33, v33
	v_mul_f32_e32 v45, v3, v3
	v_mul_f32_e32 v46, v5, v5
	v_mul_f32_e32 v47, v7, v7
	v_mul_f32_e32 v48, v9, v9
	v_fmac_f32_e32 v1, v30, v30
	v_fmac_f32_e32 v44, v32, v32
	v_fmac_f32_e32 v45, v2, v2
	v_fmac_f32_e32 v46, v4, v4
	v_mul_f32_e32 v49, v11, v11
	v_mul_f32_e32 v50, v13, v13
	v_fmac_f32_e32 v47, v6, v6
	v_fmac_f32_e32 v48, v8, v8
	v_add_f32_e32 v1, v1, v44
	v_add_f32_e32 v44, v45, v46
	v_mul_f32_e32 v51, v15, v15
	v_mul_f32_e32 v52, v17, v17
	v_fmac_f32_e32 v49, v10, v10
	v_fmac_f32_e32 v50, v12, v12
	v_add_f32_e32 v45, v47, v48
	v_add_f32_e32 v1, v1, v44
	v_mul_f32_e32 v53, v19, v19
	v_mul_f32_e32 v54, v21, v21
	v_fmac_f32_e32 v51, v14, v14
	v_fmac_f32_e32 v52, v16, v16
	v_add_f32_e32 v46, v49, v50
	v_add_f32_e32 v1, v1, v45
	v_mul_f32_e32 v55, v23, v23
	v_mul_f32_e32 v56, v25, v25
	v_fmac_f32_e32 v53, v18, v18
	v_fmac_f32_e32 v54, v20, v20
	v_add_f32_e32 v47, v51, v52
	v_add_f32_e32 v1, v1, v46
	v_mul_f32_e32 v57, v27, v27
	v_mul_f32_e32 v58, v29, v29
	v_fmac_f32_e32 v55, v22, v22
	v_fmac_f32_e32 v56, v24, v24
	v_add_f32_e32 v48, v53, v54
	v_add_f32_e32 v1, v1, v47
	v_fmac_f32_e32 v57, v26, v26
	v_fmac_f32_e32 v58, v28, v28
	v_add_f32_e32 v49, v55, v56
	v_add_f32_e32 v1, v1, v48
	v_add_f32_e32 v1, v1, v49
	v_add_f32_e32 v44, v57, v58
	v_add_f32_e32 v1, v1, v44
	s_nop 1
	v_mov_b32_dpp v44, v1 quad_perm:[1,0,3,2] row_mask:0xf bank_mask:0xf
	s_waitcnt lgkmcnt(0)
	v_add_f32_e32 v1, v1, v44
	s_nop 1
	v_mov_b32_dpp v44, v1 quad_perm:[2,3,0,1] row_mask:0xf bank_mask:0xf
	s_waitcnt lgkmcnt(0)
	v_add_f32_e32 v1, v1, v44
	s_nop 1
	v_mov_b32_dpp v44, v1 row_half_mirror row_mask:0xf bank_mask:0xf
	s_waitcnt lgkmcnt(0)
	v_add_f32_e32 v1, v1, v44
	s_nop 1
	v_mov_b32_dpp v44, v1 row_mirror row_mask:0xf bank_mask:0xf
	s_waitcnt lgkmcnt(0)
	v_add_f32_e32 v1, v1, v44
	v_mov_b32_e32 v44, v1
	s_nop 1
	v_permlane16_swap_b32_e32 v44, v1
	s_waitcnt lgkmcnt(0)
	v_add_f32_e32 v1, v1, v44
	v_mov_b32_e32 v44, v1
	s_nop 1
	v_permlane32_swap_b32_e32 v44, v1
	s_and_saveexec_b64 s[18:19], s[6:7]
	s_cbranch_execz .LBB0_568
	s_add_u32 s22, s0, s20
	s_waitcnt lgkmcnt(0)
	v_add_f32_e32 v1, v1, v44
	s_addc_u32 s23, s1, s21
	global_store_dword v197, v1, s[22:23]
	s_branch .LBB0_568
